# k52: k51 + in-projection sample-row epilogue 8-lane sums via DPP instead of ds_bpermute
# baseline (speedup 1.0000x reference)
; #define LAS __attribute__((address_space(3)))
; __device__ __forceinline__ float siluf_(float x) { return x * __builtin_amdgcn_rcpf(1.f + __expf(-x)); }
; __device__ __forceinline__ int fresh_tid() { int t = threadIdx.x; asm volatile("" : "+v"(t)); return t; }
; __global__ void __launch_bounds__(NTHR, 2) hymba_fwd(Params P) {
;     ...
;             const int tid = fresh_tid();
; #pragma unroll
;             for (int ps = 0; ps < 2; ++ps) {
;                 const int task = tid + 512 * ps; const bool ok = task < 768; const int tk = ok ? task : 0;
;                 const int row = tk / 24, ch = tk % 24, n = 192 * ns + 8 * ch, type = n >> 9, cb = n & 511, d0 = n & 63;
;                 const f32x4 c0 = *(const LAS f32x4*)(Cs + row * ldc + 8 * ch), c1 = *(const LAS f32x4*)(Cs + row * ldc + 8 * ch + 4);
;                 float v[8] = {c0[0], c0[1], c0[2], c0[3], c1[0], c1[1], c1[2], c1[3]};
;                 float ss = 0.f;
; #pragma unroll
;                 for (int e = 0; e < 8; ++e) ss += v[e] * v[e];
;                 ss += __shfl_xor(ss, 1); ss += __shfl_xor(ss, 2); ss += __shfl_xor(ss, 4);
;                 if (ok) {
;                     const int sidx = 32 * mb + row, m = PT + sidx, b = sidx >> 6, t = sidx & 63;
;                     if (type == 2 || type == 3) { const float rs = rsqrtf(ss * (1.f / 64.f) + NORM_EPS); const float* gp = (type == 2) ? P.q_g : P.k_g;
; #pragma unroll
;                         for (int e = 0; e < 8; ++e) v[e] = v[e] * rs * gp[d0 + e] * (type == 2 ? C2 : 1.f); }
;                     else if (type == 1 || type == 5) {
; #pragma unroll
;                         for (int e = 0; e < 8; ++e) v[e] = siluf_(v[e]); }
.LBB0_214:
	v_mov_b32_e32 v16, v208
	s_movk_i32 s0, 0x300
	s_waitcnt lgkmcnt(0)
	s_barrier
	v_and_b32_e32 v0, 64, v114
	v_cmp_gt_i32_e32 vcc, s0, v16
	v_add_u32_e32 v8, 64, v0
	v_xor_b32_e32 v4, 1, v114
	v_cndmask_b32_e32 v0, 0, v16, vcc
	v_mul_hi_i32 v1, v0, s33
	v_lshrrev_b32_e32 v2, 31, v1
	v_ashrrev_i32_e32 v1, 2, v1
	v_add_u32_e32 v13, v1, v2
	v_mul_lo_u32 v1, v13, 24
	v_sub_u32_e32 v10, v0, v1
	v_mul_lo_u32 v0, v13, s3
	v_lshlrev_b32_e32 v1, 5, v10
	v_add3_u32 v5, 0, v0, v1
	ds_read_b128 v[0:3], v5
	v_cmp_lt_i32_e64 s[0:1], v4, v8
	v_xor_b32_e32 v12, 2, v114
	s_waitcnt lgkmcnt(0)
	v_mul_f32_e32 v9, v1, v1
	v_cndmask_b32_e64 v4, v114, v4, s[0:1]
	v_lshlrev_b32_e32 v17, 2, v4
	ds_read_b128 v[4:7], v5 offset:16
	v_fmac_f32_e32 v9, v0, v0
	v_fmac_f32_e32 v9, v2, v2
	v_fmac_f32_e32 v9, v3, v3
	v_cmp_lt_i32_e64 s[0:1], v12, v8
	s_waitcnt lgkmcnt(0)
	v_fmac_f32_e32 v9, v4, v4
	v_fmac_f32_e32 v9, v5, v5
	v_fmac_f32_e32 v9, v6, v6
	v_fmac_f32_e32 v9, v7, v7
	s_nop 1
	v_mov_b32_dpp v11, v9 quad_perm:[1,0,3,2] row_mask:0xf bank_mask:0xf
	v_cndmask_b32_e64 v12, v114, v12, s[0:1]
	v_lshlrev_b32_e32 v18, 2, v12
	v_xor_b32_e32 v12, 4, v114
	v_cmp_lt_i32_e64 s[0:1], v12, v8
	s_waitcnt lgkmcnt(0)
	v_add_f32_e32 v9, v9, v11
	s_nop 1
	v_mov_b32_dpp v11, v9 quad_perm:[2,3,0,1] row_mask:0xf bank_mask:0xf
	v_cndmask_b32_e64 v8, v114, v12, s[0:1]
	v_lshlrev_b32_e32 v19, 2, v8
	s_waitcnt lgkmcnt(0)
	v_add_f32_e32 v8, v9, v11
	s_nop 1
	v_mov_b32_dpp v9, v8 row_half_mirror row_mask:0xf bank_mask:0xf
	s_and_saveexec_b64 s[20:21], vcc
	s_cbranch_execz .LBB0_239
	v_lshlrev_b32_e32 v15, 3, v10
	v_add_u32_e32 v20, s6, v15
	v_ashrrev_i32_e32 v21, 9, v20
	v_and_b32_e32 v10, 0xfffffc00, v20
	v_cmp_eq_u32_e64 s[0:1], 2, v21
	v_cmp_ne_u32_e32 vcc, 2, v21
	v_cmp_ne_u32_e64 s[4:5], s34, v10
	s_and_saveexec_b64 s[28:29], s[4:5]
	s_xor_b64 s[28:29], exec, s[28:29]
	s_cbranch_execz .LBB0_219
	v_and_b32_e32 v8, 0xfffff600, v20
	v_cmp_eq_u32_e64 s[4:5], s35, v8
	s_and_saveexec_b64 s[30:31], s[4:5]
	s_cbranch_execz .LBB0_218
	v_mul_f32_e32 v12, 0xbfb8aa3b, v4
	v_exp_f32_e32 v12, v12
	v_mul_f32_e32 v14, 0xbfb8aa3b, v6
	v_mul_f32_e32 v8, 0xbfb8aa3b, v0
	s_waitcnt lgkmcnt(0)
	v_mul_f32_e32 v9, 0xbfb8aa3b, v1
	v_add_f32_e32 v12, 1.0, v12
	v_mul_f32_e32 v10, 0xbfb8aa3b, v2
	v_mul_f32_e32 v11, 0xbfb8aa3b, v3
	v_rcp_f32_e32 v22, v12
	v_mul_f32_e32 v12, 0xbfb8aa3b, v5
	v_exp_f32_e32 v14, v14
	v_mul_f32_e32 v23, 0xbfb8aa3b, v7
	v_exp_f32_e32 v8, v8
	v_exp_f32_e32 v9, v9
	v_exp_f32_e32 v10, v10
	v_exp_f32_e32 v11, v11
	v_exp_f32_e32 v12, v12
	v_exp_f32_e32 v23, v23
	v_add_f32_e32 v14, 1.0, v14
	v_add_f32_e32 v8, 1.0, v8
	v_add_f32_e32 v9, 1.0, v9
	v_add_f32_e32 v10, 1.0, v10
	v_add_f32_e32 v11, 1.0, v11
	v_add_f32_e32 v12, 1.0, v12
	v_rcp_f32_e32 v24, v14
	v_add_f32_e32 v14, 1.0, v23
	v_rcp_f32_e32 v8, v8
	v_rcp_f32_e32 v9, v9
	v_rcp_f32_e32 v10, v10
	v_rcp_f32_e32 v11, v11
	v_rcp_f32_e32 v25, v14
	v_rcp_f32_e32 v23, v12
	v_pk_mul_f32 v[0:1], v[0:1], v[8:9]
	v_pk_mul_f32 v[2:3], v[2:3], v[10:11]
	v_pk_mul_f32 v[6:7], v[6:7], v[24:25]
	v_pk_mul_f32 v[4:5], v[4:5], v[22:23]

; #define LAS __attribute__((address_space(3)))
; __device__ __forceinline__ float siluf_(float x) { return x * __builtin_amdgcn_rcpf(1.f + __expf(-x)); }
; __global__ void __launch_bounds__(NTHR, 2) hymba_fwd(Params P) {
;     ...
;             for (int ps = 0; ps < 2; ++ps) {
;                 const int task = tid + 512 * ps; const bool ok = task < 768; const int tk = ok ? task : 0;
;                 const int row = tk / 24, ch = tk % 24, n = 192 * ns + 8 * ch, type = n >> 9, cb = n & 511, d0 = n & 63;
;                 const f32x4 c0 = *(const LAS f32x4*)(Cs + row * ldc + 8 * ch), c1 = *(const LAS f32x4*)(Cs + row * ldc + 8 * ch + 4);
;                 float v[8] = {c0[0], c0[1], c0[2], c0[3], c1[0], c1[1], c1[2], c1[3]};
;                 float ss = 0.f;
; #pragma unroll
;                 for (int e = 0; e < 8; ++e) ss += v[e] * v[e];
;                 ss += __shfl_xor(ss, 1); ss += __shfl_xor(ss, 2); ss += __shfl_xor(ss, 4);
;                 if (ok) {
;                     const int sidx = 32 * mb + row, m = PT + sidx, b = sidx >> 6, t = sidx & 63;
;                     if (type == 2 || type == 3) { const float rs = rsqrtf(ss * (1.f / 64.f) + NORM_EPS); const float* gp = (type == 2) ? P.q_g : P.k_g;
; #pragma unroll
;                         for (int e = 0; e < 8; ++e) v[e] = v[e] * rs * gp[d0 + e] * (type == 2 ? C2 : 1.f); }
;                     else if (type == 1 || type == 5) {
; #pragma unroll
;                         for (int e = 0; e < 8; ++e) v[e] = siluf_(v[e]); }
.LBB0_239:
	s_or_b64 exec, exec, s[20:21]
	s_movk_i32 s0, 0x100
	v_add_u32_e32 v0, 0x200, v16
	v_cmp_gt_i32_e32 vcc, s0, v16
	s_nop 1
	v_cndmask_b32_e32 v0, 0, v0, vcc
	v_mul_hi_i32 v1, v0, s33
	v_lshrrev_b32_e32 v2, 31, v1
	v_ashrrev_i32_e32 v1, 2, v1
	v_add_u32_e32 v13, v1, v2
	v_mul_lo_u32 v1, v13, 24
	v_sub_u32_e32 v10, v0, v1
	v_mul_lo_u32 v0, v13, s3
	v_lshlrev_b32_e32 v1, 5, v10
	v_add3_u32 v0, 0, v0, v1
	ds_read_b128 v[4:7], v0
	ds_read_b128 v[0:3], v0 offset:16
	s_waitcnt lgkmcnt(1)
	v_mul_f32_e32 v8, v5, v5
	v_fmac_f32_e32 v8, v4, v4
	v_fmac_f32_e32 v8, v6, v6
	v_fmac_f32_e32 v8, v7, v7
	s_waitcnt lgkmcnt(0)
	v_fmac_f32_e32 v8, v0, v0
	v_fmac_f32_e32 v8, v1, v1
	v_fmac_f32_e32 v8, v2, v2
	v_fmac_f32_e32 v8, v3, v3
	s_nop 1
	v_mov_b32_dpp v9, v8 quad_perm:[1,0,3,2] row_mask:0xf bank_mask:0xf
	s_waitcnt lgkmcnt(0)
	v_add_f32_e32 v8, v8, v9
	s_nop 1
	v_mov_b32_dpp v9, v8 quad_perm:[2,3,0,1] row_mask:0xf bank_mask:0xf
	s_waitcnt lgkmcnt(0)
	v_add_f32_e32 v8, v8, v9
	s_nop 1
	v_mov_b32_dpp v9, v8 row_half_mirror row_mask:0xf bank_mask:0xf
	s_and_saveexec_b64 s[20:21], vcc
	s_cbranch_execz .LBB0_205
	v_lshlrev_b32_e32 v15, 3, v10
	v_add_u32_e32 v16, s6, v15
	v_ashrrev_i32_e32 v17, 9, v16
	v_and_b32_e32 v10, 0xfffffc00, v16
	v_cmp_eq_u32_e64 s[0:1], 2, v17
	v_cmp_ne_u32_e32 vcc, 2, v17
	v_cmp_ne_u32_e64 s[4:5], s34, v10
	s_and_saveexec_b64 s[28:29], s[4:5]
	s_xor_b64 s[28:29], exec, s[28:29]
	s_cbranch_execz .LBB0_244
	v_and_b32_e32 v8, 0xfffff600, v16
	v_cmp_eq_u32_e64 s[4:5], s35, v8
	s_and_saveexec_b64 s[30:31], s[4:5]
	s_cbranch_execz .LBB0_243
	v_mul_f32_e32 v12, 0xbfb8aa3b, v0
	v_exp_f32_e32 v12, v12
	v_mul_f32_e32 v14, 0xbfb8aa3b, v2
	v_mul_f32_e32 v8, 0xbfb8aa3b, v4
	s_waitcnt lgkmcnt(0)
	v_mul_f32_e32 v9, 0xbfb8aa3b, v5
	v_add_f32_e32 v12, 1.0, v12
	v_mul_f32_e32 v10, 0xbfb8aa3b, v6
	v_mul_f32_e32 v11, 0xbfb8aa3b, v7
	v_rcp_f32_e32 v18, v12
	v_mul_f32_e32 v12, 0xbfb8aa3b, v1
	v_exp_f32_e32 v14, v14
	v_mul_f32_e32 v19, 0xbfb8aa3b, v3
	v_exp_f32_e32 v8, v8
	v_exp_f32_e32 v9, v9
	v_exp_f32_e32 v10, v10
	v_exp_f32_e32 v11, v11
	v_exp_f32_e32 v12, v12
	v_exp_f32_e32 v19, v19
	v_add_f32_e32 v14, 1.0, v14
	v_add_f32_e32 v8, 1.0, v8
	v_add_f32_e32 v9, 1.0, v9
	v_add_f32_e32 v10, 1.0, v10
	v_add_f32_e32 v11, 1.0, v11
	v_add_f32_e32 v12, 1.0, v12
	v_rcp_f32_e32 v20, v14
	v_add_f32_e32 v14, 1.0, v19
	v_rcp_f32_e32 v8, v8
	v_rcp_f32_e32 v9, v9
	v_rcp_f32_e32 v10, v10
	v_rcp_f32_e32 v11, v11
	v_rcp_f32_e32 v21, v14
	v_rcp_f32_e32 v19, v12
	v_pk_mul_f32 v[4:5], v[4:5], v[8:9]
	v_pk_mul_f32 v[6:7], v[6:7], v[10:11]
	v_pk_mul_f32 v[2:3], v[2:3], v[20:21]
	v_pk_mul_f32 v[0:1], v[0:1], v[18:19]
